# GEMM k-loop: next-iteration address select hoisted into phase-4 load segment tail, branch-free
# speedup vs baseline: 1.0125x; 1.0125x over previous
; #define PG8_STAGE(bufoff, gbase, voff) do { _Pragma("unroll") for (int _i = 0; _i < 2; ++_i) \
;         __builtin_amdgcn_global_load_lds((const unsigned*)((const char*)(gbase) + (voff)[_i]), (LAS unsigned*)(lds + (bufoff) + ldsw + _i * 8192), 16, 0, 0); } while (0)
; #define PG8_LDA(dst, b, h) do { _Pragma("unroll") for (int m = 0; m < 4; ++m) _Pragma("unroll") for (int k = 0; k < 2; ++k) dst[m][k] = *(const LAS bf16x8*)(lds + PG8_SA(b, h) + aoff + m * 2048 + k * 1024); } while (0)
; #define PG8_LDB(dst, b, h) do { _Pragma("unroll") for (int n = 0; n < 2; ++n) _Pragma("unroll") for (int k = 0; k < 2; ++k) dst[n][k] = *(const LAS bf16x8*)(lds + PG8_SB(b, h) + boff + n * 2048 + k * 1024); } while (0)
; #define PG8_MMA(ai, bj, At, Bt) do { __builtin_amdgcn_s_setprio(1); _Pragma("unroll") for (int m = 0; m < 4; ++m) _Pragma("unroll") for (int n = 0; n < 2; ++n) _Pragma("unroll") for (int k = 0; k < 2; ++k) \
;         acc[ai][bj][m][n] = __builtin_amdgcn_mfma_f32_16x16x32_bf16(Bt[n][k], At[m][k], acc[ai][bj][m][n], 0, 0, 0); __builtin_amdgcn_s_setprio(0); } while (0)
; #define PG8_WAIT_V(n) asm volatile("s_waitcnt vmcnt(" #n ")" ::: "memory")
; #define PG8_WAIT_L(n) asm volatile("s_waitcnt lgkmcnt(" #n ")" ::: "memory")
; #define PG8_BAR __builtin_amdgcn_s_barrier()
; #define PG8_SCHED __builtin_amdgcn_sched_barrier(0)
; __device__ __forceinline__ void gemm_generic(LAS unsigned char* lds, const GDesc& d, int G, int bx) {
;     ...
;         for (int t = 0; t < nt; t += 2) {
;             const bool last = (t == nt - 2);
;             const char* a1 = cA + a_koff(d, t + 1);
;             const char* a2 = last ? nA : cA + a_koff(d, t + 2); const char* b2 = last ? nB : cB + (size_t)(t + 2) * kstep;
;             const char* a3 = last ? nA + a_koff(d, 1) : cA + a_koff(d, t + 3); const char* b3 = b2 + kstep;
;             PG8_LDB(B0, 0, 0); PG8_LDB(B1, 0, 1); PG8_SCHED; PG8_LDA(At, 0, 0); PG8_STAGE(PG8_SA(1, 1), a1 + hstepA, voffA);
;             PG8_WAIT_V(8); PG8_WAIT_L(0); PG8_BAR; PG8_MMA(0, 0, At, B0); PG8_MMA(0, 1, At, B1); PG8_BAR; PG8_SCHED;
;             PG8_LDA(At, 0, 1); PG8_STAGE(PG8_SB(0, 0), b2, voffB); PG8_STAGE(PG8_SB(0, 1), b2 + hstepB, voffB); PG8_STAGE(PG8_SA(0, 0), a2, voffA);
;             PG8_WAIT_V(8); PG8_WAIT_L(0); PG8_BAR; PG8_MMA(1, 0, At, B0); PG8_MMA(1, 1, At, B1); PG8_BAR; PG8_SCHED;
.Lg_body:
	s_add_i32 s17, 0, 0x10000
	s_add_i32 s26, 0, 0x14000
	v_add_u32_e32 v142, s17, v231
	v_add_u32_e32 v158, s26, v231
	ds_read_b128 v[130:133], v142
	ds_read_b128 v[134:137], v142 offset:1024
	ds_read_b128 v[138:141], v142 offset:2048
	ds_read_b128 v[142:145], v142 offset:3072
	ds_read_b128 v[146:149], v158
	ds_read_b128 v[150:153], v158 offset:1024
	ds_read_b128 v[154:157], v158 offset:2048
	ds_read_b128 v[158:161], v158 offset:3072
	s_add_u32 s34, s12, s34
	s_addc_u32 s35, s13, s35
	v_lshl_add_u64 v[208:209], s[34:35], 0, v[198:199]
	s_add_i32 m0, s97, 0xc000
	ds_read_b128 v[162:165], v232
	ds_read_b128 v[166:169], v232 offset:1024
	ds_read_b128 v[170:173], v232 offset:2048
	ds_read_b128 v[174:177], v232 offset:3072
	ds_read_b128 v[178:181], v232 offset:4096
	ds_read_b128 v[182:185], v232 offset:5120
	ds_read_b128 v[186:189], v232 offset:6144
	ds_read_b128 v[190:193], v232 offset:7168
	global_load_lds_dwordx4 v[208:209], off
	v_lshl_add_u64 v[208:209], s[34:35], 0, v[202:203]
	s_add_i32 m0, s97, 0xe000
	s_nop 0
	global_load_lds_dwordx4 v[208:209], off
	s_waitcnt vmcnt(8)
	s_waitcnt lgkmcnt(0)
	s_barrier
	s_setprio 1
	s_waitcnt lgkmcnt(0)
	v_mfma_f32_16x16x32_bf16 v[124:127], v[130:133], v[162:165], v[124:127]
	v_mfma_f32_16x16x32_bf16 v[120:123], v[138:141], v[162:165], v[120:123]
	v_mfma_f32_16x16x32_bf16 v[112:115], v[130:133], v[170:173], v[112:115]
	v_mfma_f32_16x16x32_bf16 v[104:107], v[138:141], v[170:173], v[104:107]
	v_mfma_f32_16x16x32_bf16 v[96:99], v[130:133], v[178:181], v[96:99]
	v_mfma_f32_16x16x32_bf16 v[88:91], v[138:141], v[178:181], v[88:91]
	v_mfma_f32_16x16x32_bf16 v[80:83], v[130:133], v[186:189], v[80:83]
	v_mfma_f32_16x16x32_bf16 v[72:75], v[138:141], v[186:189], v[72:75]
	v_mfma_f32_16x16x32_bf16 v[124:127], v[134:137], v[166:169], v[124:127]
	v_mfma_f32_16x16x32_bf16 v[120:123], v[142:145], v[166:169], v[120:123]
	v_mfma_f32_16x16x32_bf16 v[112:115], v[134:137], v[174:177], v[112:115]
	v_mfma_f32_16x16x32_bf16 v[104:107], v[142:145], v[174:177], v[104:107]
	v_mfma_f32_16x16x32_bf16 v[96:99], v[134:137], v[182:185], v[96:99]
	v_mfma_f32_16x16x32_bf16 v[88:91], v[142:145], v[182:185], v[88:91]
	v_mfma_f32_16x16x32_bf16 v[80:83], v[134:137], v[190:193], v[80:83]
	v_mfma_f32_16x16x32_bf16 v[72:75], v[142:145], v[190:193], v[72:75]
	s_setprio 0
	s_setprio 1
	v_mfma_f32_16x16x32_bf16 v[116:119], v[146:149], v[162:165], v[116:119]
	v_mfma_f32_16x16x32_bf16 v[108:111], v[154:157], v[162:165], v[108:111]
	v_mfma_f32_16x16x32_bf16 v[100:103], v[146:149], v[170:173], v[100:103]
	v_mfma_f32_16x16x32_bf16 v[92:95], v[154:157], v[170:173], v[92:95]
	v_mfma_f32_16x16x32_bf16 v[84:87], v[146:149], v[178:181], v[84:87]
	v_mfma_f32_16x16x32_bf16 v[76:79], v[154:157], v[178:181], v[76:79]
	v_mfma_f32_16x16x32_bf16 v[68:71], v[146:149], v[186:189], v[68:71]
	v_mfma_f32_16x16x32_bf16 v[64:67], v[154:157], v[186:189], v[64:67]
	v_mfma_f32_16x16x32_bf16 v[116:119], v[150:153], v[166:169], v[116:119]
	v_mfma_f32_16x16x32_bf16 v[108:111], v[158:161], v[166:169], v[108:111]
	v_mfma_f32_16x16x32_bf16 v[100:103], v[150:153], v[174:177], v[100:103]
	v_mfma_f32_16x16x32_bf16 v[92:95], v[158:161], v[174:177], v[92:95]
	v_mfma_f32_16x16x32_bf16 v[84:87], v[150:153], v[182:185], v[84:87]
	v_mfma_f32_16x16x32_bf16 v[76:79], v[158:161], v[182:185], v[76:79]
	v_mfma_f32_16x16x32_bf16 v[68:71], v[150:153], v[190:193], v[68:71]
	v_mfma_f32_16x16x32_bf16 v[64:67], v[158:161], v[190:193], v[64:67]
	s_setprio 0
	s_barrier
	s_add_i32 s17, s17, s95
	v_lshl_add_u64 v[208:209], s[44:45], 0, v[200:201]
	s_mov_b32 m0, s17
	ds_read_b128 v[162:165], v232 offset:16384
	ds_read_b128 v[166:169], v232 offset:17408
	ds_read_b128 v[170:173], v232 offset:18432
	ds_read_b128 v[174:177], v232 offset:19456
	ds_read_b128 v[178:181], v232 offset:20480
	ds_read_b128 v[182:185], v232 offset:21504
	ds_read_b128 v[186:189], v232 offset:22528
	ds_read_b128 v[190:193], v232 offset:23552
	global_load_lds_dwordx4 v[208:209], off
	s_add_i32 m0, s17, 0x2000
	s_add_u32 s34, s44, s76
	v_lshl_add_u64 v[210:211], s[44:45], 0, v[204:205]
	s_addc_u32 s35, s45, s77
	s_add_i32 s17, s26, s95
	global_load_lds_dwordx4 v[210:211], off
	v_lshl_add_u64 v[212:213], s[34:35], 0, v[200:201]
	s_mov_b32 m0, s17
	v_lshl_add_u64 v[214:215], s[34:35], 0, v[204:205]
	global_load_lds_dwordx4 v[212:213], off
	s_add_i32 m0, s17, 0x2000
	v_lshl_add_u64 v[216:217], s[28:29], 0, v[198:199]
	global_load_lds_dwordx4 v[214:215], off
	s_mov_b32 m0, s97
	s_nop 0
	global_load_lds_dwordx4 v[216:217], off
	v_lshl_add_u64 v[216:217], s[28:29], 0, v[202:203]
	s_mov_b32 m0, s27
	s_nop 0
	global_load_lds_dwordx4 v[216:217], off
	s_waitcnt vmcnt(8)
	s_waitcnt lgkmcnt(0)
	s_barrier
; #define PG8_STAGE(bufoff, gbase, voff) do { _Pragma("unroll") for (int _i = 0; _i < 2; ++_i) \
;         __builtin_amdgcn_global_load_lds((const unsigned*)((const char*)(gbase) + (voff)[_i]), (LAS unsigned*)(lds + (bufoff) + ldsw + _i * 8192), 16, 0, 0); } while (0)
; #define PG8_LDA(dst, b, h) do { _Pragma("unroll") for (int m = 0; m < 4; ++m) _Pragma("unroll") for (int k = 0; k < 2; ++k) dst[m][k] = *(const LAS bf16x8*)(lds + PG8_SA(b, h) + aoff + m * 2048 + k * 1024); } while (0)
; #define PG8_LDB(dst, b, h) do { _Pragma("unroll") for (int n = 0; n < 2; ++n) _Pragma("unroll") for (int k = 0; k < 2; ++k) dst[n][k] = *(const LAS bf16x8*)(lds + PG8_SB(b, h) + boff + n * 2048 + k * 1024); } while (0)
; #define PG8_MMA(ai, bj, At, Bt) do { __builtin_amdgcn_s_setprio(1); _Pragma("unroll") for (int m = 0; m < 4; ++m) _Pragma("unroll") for (int n = 0; n < 2; ++n) _Pragma("unroll") for (int k = 0; k < 2; ++k) \
;         acc[ai][bj][m][n] = __builtin_amdgcn_mfma_f32_16x16x32_bf16(Bt[n][k], At[m][k], acc[ai][bj][m][n], 0, 0, 0); __builtin_amdgcn_s_setprio(0); } while (0)
; #define PG8_WAIT_V(n) asm volatile("s_waitcnt vmcnt(" #n ")" ::: "memory")
; #define PG8_WAIT_L(n) asm volatile("s_waitcnt lgkmcnt(" #n ")" ::: "memory")
; #define PG8_BAR __builtin_amdgcn_s_barrier()
; #define PG8_SCHED __builtin_amdgcn_sched_barrier(0)
; __device__ __forceinline__ void gemm_generic(LAS unsigned char* lds, const GDesc& d, int G, int bx) {
;     ...
;             PG8_WAIT_V(8); PG8_WAIT_L(0); PG8_BAR; PG8_MMA(1, 0, At, B0); PG8_MMA(1, 1, At, B1); PG8_BAR; PG8_SCHED;
;             PG8_LDB(B0, 1, 0); PG8_LDB(B1, 1, 1); PG8_SCHED; PG8_LDA(At, 1, 0); PG8_STAGE(PG8_SA(0, 1), a2 + hstepA, voffA);
;             PG8_WAIT_V(8); PG8_WAIT_L(0); PG8_BAR; PG8_MMA(0, 0, At, B0); PG8_MMA(0, 1, At, B1); PG8_BAR; PG8_SCHED;
	s_setprio 1
	s_waitcnt lgkmcnt(0)
	v_mfma_f32_16x16x32_bf16 v[60:63], v[130:133], v[162:165], v[60:63]
	v_mfma_f32_16x16x32_bf16 v[56:59], v[138:141], v[162:165], v[56:59]
	v_mfma_f32_16x16x32_bf16 v[48:51], v[130:133], v[170:173], v[48:51]
	v_mfma_f32_16x16x32_bf16 v[40:43], v[138:141], v[170:173], v[40:43]
	v_mfma_f32_16x16x32_bf16 v[32:35], v[130:133], v[178:181], v[32:35]
	v_mfma_f32_16x16x32_bf16 v[24:27], v[138:141], v[178:181], v[24:27]
	v_mfma_f32_16x16x32_bf16 v[16:19], v[130:133], v[186:189], v[16:19]
	v_mfma_f32_16x16x32_bf16 v[8:11], v[138:141], v[186:189], v[8:11]
	v_mfma_f32_16x16x32_bf16 v[60:63], v[134:137], v[166:169], v[60:63]
	v_mfma_f32_16x16x32_bf16 v[56:59], v[142:145], v[166:169], v[56:59]
	v_mfma_f32_16x16x32_bf16 v[48:51], v[134:137], v[174:177], v[48:51]
	v_mfma_f32_16x16x32_bf16 v[40:43], v[142:145], v[174:177], v[40:43]
	v_mfma_f32_16x16x32_bf16 v[32:35], v[134:137], v[182:185], v[32:35]
	v_mfma_f32_16x16x32_bf16 v[24:27], v[142:145], v[182:185], v[24:27]
	v_mfma_f32_16x16x32_bf16 v[16:19], v[134:137], v[190:193], v[16:19]
	v_mfma_f32_16x16x32_bf16 v[8:11], v[142:145], v[190:193], v[8:11]
	s_setprio 0
	s_setprio 1
	v_mfma_f32_16x16x32_bf16 v[52:55], v[146:149], v[162:165], v[52:55]
	v_mfma_f32_16x16x32_bf16 v[44:47], v[154:157], v[162:165], v[44:47]
	v_mfma_f32_16x16x32_bf16 v[36:39], v[146:149], v[170:173], v[36:39]
	v_mfma_f32_16x16x32_bf16 v[28:31], v[154:157], v[170:173], v[28:31]
	v_mfma_f32_16x16x32_bf16 v[20:23], v[146:149], v[178:181], v[20:23]
	v_mfma_f32_16x16x32_bf16 v[12:15], v[154:157], v[178:181], v[12:15]
	v_mfma_f32_16x16x32_bf16 v[4:7], v[146:149], v[186:189], v[4:7]
	v_mfma_f32_16x16x32_bf16 v[0:3], v[154:157], v[186:189], v[0:3]
	v_mfma_f32_16x16x32_bf16 v[52:55], v[150:153], v[166:169], v[52:55]
	v_mfma_f32_16x16x32_bf16 v[44:47], v[158:161], v[166:169], v[44:47]
	v_mfma_f32_16x16x32_bf16 v[36:39], v[150:153], v[174:177], v[36:39]
	v_mfma_f32_16x16x32_bf16 v[28:31], v[158:161], v[174:177], v[28:31]
	v_mfma_f32_16x16x32_bf16 v[20:23], v[150:153], v[182:185], v[20:23]
	v_mfma_f32_16x16x32_bf16 v[12:15], v[158:161], v[182:185], v[12:15]
	v_mfma_f32_16x16x32_bf16 v[4:7], v[150:153], v[190:193], v[4:7]
	v_mfma_f32_16x16x32_bf16 v[0:3], v[158:161], v[190:193], v[0:3]
	s_setprio 0
	s_barrier
	s_add_i32 s17, 0, 0x18000
	s_add_i32 s26, 0, 0x1c000
	v_add_u32_e32 v142, s17, v231
	v_add_u32_e32 v158, s26, v231
	ds_read_b128 v[130:133], v142
	ds_read_b128 v[134:137], v142 offset:1024
	ds_read_b128 v[138:141], v142 offset:2048
	ds_read_b128 v[142:145], v142 offset:3072
	ds_read_b128 v[146:149], v158
	ds_read_b128 v[150:153], v158 offset:1024
	ds_read_b128 v[154:157], v158 offset:2048
	ds_read_b128 v[158:161], v158 offset:3072
	s_add_u32 s28, s28, s74
	s_addc_u32 s29, s29, s75
	s_mov_b32 m0, s64
	v_lshl_add_u64 v[216:217], s[28:29], 0, v[198:199]
	ds_read_b128 v[162:165], v232 offset:32768
	ds_read_b128 v[166:169], v232 offset:33792
	ds_read_b128 v[170:173], v232 offset:34816
	ds_read_b128 v[174:177], v232 offset:35840
	ds_read_b128 v[178:181], v232 offset:36864
	ds_read_b128 v[182:185], v232 offset:37888
	ds_read_b128 v[186:189], v232 offset:38912
	ds_read_b128 v[190:193], v232 offset:39936
	global_load_lds_dwordx4 v[216:217], off
	v_lshl_add_u64 v[216:217], s[28:29], 0, v[202:203]
	s_mov_b32 m0, s65
	s_nop 0
	global_load_lds_dwordx4 v[216:217], off
	s_waitcnt vmcnt(8)
	s_waitcnt lgkmcnt(0)
	s_barrier
	s_setprio 1
	s_waitcnt lgkmcnt(0)
	v_mfma_f32_16x16x32_bf16 v[124:127], v[130:133], v[162:165], v[124:127]
	v_mfma_f32_16x16x32_bf16 v[120:123], v[138:141], v[162:165], v[120:123]
	v_mfma_f32_16x16x32_bf16 v[112:115], v[130:133], v[170:173], v[112:115]
	v_mfma_f32_16x16x32_bf16 v[104:107], v[138:141], v[170:173], v[104:107]
	v_mfma_f32_16x16x32_bf16 v[96:99], v[130:133], v[178:181], v[96:99]
	v_mfma_f32_16x16x32_bf16 v[88:91], v[138:141], v[178:181], v[88:91]
	v_mfma_f32_16x16x32_bf16 v[80:83], v[130:133], v[186:189], v[80:83]
	v_mfma_f32_16x16x32_bf16 v[72:75], v[138:141], v[186:189], v[72:75]
	v_mfma_f32_16x16x32_bf16 v[124:127], v[134:137], v[166:169], v[124:127]
	v_mfma_f32_16x16x32_bf16 v[120:123], v[142:145], v[166:169], v[120:123]
	v_mfma_f32_16x16x32_bf16 v[112:115], v[134:137], v[174:177], v[112:115]
	v_mfma_f32_16x16x32_bf16 v[104:107], v[142:145], v[174:177], v[104:107]
	v_mfma_f32_16x16x32_bf16 v[96:99], v[134:137], v[182:185], v[96:99]
	v_mfma_f32_16x16x32_bf16 v[88:91], v[142:145], v[182:185], v[88:91]
	v_mfma_f32_16x16x32_bf16 v[80:83], v[134:137], v[190:193], v[80:83]
	v_mfma_f32_16x16x32_bf16 v[72:75], v[142:145], v[190:193], v[72:75]
	s_setprio 0
	s_setprio 1
	v_mfma_f32_16x16x32_bf16 v[116:119], v[146:149], v[162:165], v[116:119]
	v_mfma_f32_16x16x32_bf16 v[108:111], v[154:157], v[162:165], v[108:111]
	v_mfma_f32_16x16x32_bf16 v[100:103], v[146:149], v[170:173], v[100:103]
	v_mfma_f32_16x16x32_bf16 v[92:95], v[154:157], v[170:173], v[92:95]
	v_mfma_f32_16x16x32_bf16 v[84:87], v[146:149], v[178:181], v[84:87]
	v_mfma_f32_16x16x32_bf16 v[76:79], v[154:157], v[178:181], v[76:79]
	v_mfma_f32_16x16x32_bf16 v[68:71], v[146:149], v[186:189], v[68:71]
	v_mfma_f32_16x16x32_bf16 v[64:67], v[154:157], v[186:189], v[64:67]
	v_mfma_f32_16x16x32_bf16 v[116:119], v[150:153], v[166:169], v[116:119]
	v_mfma_f32_16x16x32_bf16 v[108:111], v[158:161], v[166:169], v[108:111]
	v_mfma_f32_16x16x32_bf16 v[100:103], v[150:153], v[174:177], v[100:103]
	v_mfma_f32_16x16x32_bf16 v[92:95], v[158:161], v[174:177], v[92:95]
	v_mfma_f32_16x16x32_bf16 v[84:87], v[150:153], v[182:185], v[84:87]
	v_mfma_f32_16x16x32_bf16 v[76:79], v[158:161], v[182:185], v[76:79]
	v_mfma_f32_16x16x32_bf16 v[68:71], v[150:153], v[190:193], v[68:71]
	v_mfma_f32_16x16x32_bf16 v[64:67], v[158:161], v[190:193], v[64:67]
	s_setprio 0
	s_barrier
; #define PG8_STAGE(bufoff, gbase, voff) do { _Pragma("unroll") for (int _i = 0; _i < 2; ++_i) \
;         __builtin_amdgcn_global_load_lds((const unsigned*)((const char*)(gbase) + (voff)[_i]), (LAS unsigned*)(lds + (bufoff) + ldsw + _i * 8192), 16, 0, 0); } while (0)
; #define PG8_LDA(dst, b, h) do { _Pragma("unroll") for (int m = 0; m < 4; ++m) _Pragma("unroll") for (int k = 0; k < 2; ++k) dst[m][k] = *(const LAS bf16x8*)(lds + PG8_SA(b, h) + aoff + m * 2048 + k * 1024); } while (0)
; #define PG8_MMA(ai, bj, At, Bt) do { __builtin_amdgcn_s_setprio(1); _Pragma("unroll") for (int m = 0; m < 4; ++m) _Pragma("unroll") for (int n = 0; n < 2; ++n) _Pragma("unroll") for (int k = 0; k < 2; ++k) \
;         acc[ai][bj][m][n] = __builtin_amdgcn_mfma_f32_16x16x32_bf16(Bt[n][k], At[m][k], acc[ai][bj][m][n], 0, 0, 0); __builtin_amdgcn_s_setprio(0); } while (0)
; #define PG8_WAIT_V(n) asm volatile("s_waitcnt vmcnt(" #n ")" ::: "memory")
; #define PG8_WAIT_L(n) asm volatile("s_waitcnt lgkmcnt(" #n ")" ::: "memory")
; #define PG8_BAR __builtin_amdgcn_s_barrier()
; #define PG8_SCHED __builtin_amdgcn_sched_barrier(0)
; __device__ __forceinline__ void gemm_generic(LAS unsigned char* lds, const GDesc& d, int G, int bx) {
;     ...
;         for (int t = 0; t < nt; t += 2) {
;             const bool last = (t == nt - 2);
;             const char* a1 = cA + a_koff(d, t + 1);
;             const char* a2 = last ? nA : cA + a_koff(d, t + 2); const char* b2 = last ? nB : cB + (size_t)(t + 2) * kstep;
;             const char* a3 = last ? nA + a_koff(d, 1) : cA + a_koff(d, t + 3); const char* b3 = b2 + kstep;
;     ...
;             PG8_LDA(At, 1, 1); PG8_STAGE(PG8_SB(1, 0), b3, voffB); PG8_STAGE(PG8_SB(1, 1), b3 + hstepB, voffB); PG8_STAGE(PG8_SA(1, 0), a3, voffA);
;             PG8_WAIT_V(8); PG8_WAIT_L(0); PG8_BAR; PG8_MMA(1, 0, At, B0); PG8_MMA(1, 1, At, B1); PG8_BAR; PG8_SCHED;
	s_add_i32 s17, s17, s95
	v_lshl_add_u64 v[208:209], v[208:209], 0, s[20:21]
	s_mov_b32 m0, s17
	ds_read_b128 v[162:165], v232 offset:49152
	ds_read_b128 v[166:169], v232 offset:50176
	ds_read_b128 v[170:173], v232 offset:51200
	ds_read_b128 v[174:177], v232 offset:52224
	ds_read_b128 v[178:181], v232 offset:53248
	ds_read_b128 v[182:185], v232 offset:54272
	ds_read_b128 v[186:189], v232 offset:55296
	ds_read_b128 v[190:193], v232 offset:56320
	global_load_lds_dwordx4 v[208:209], off
	v_lshl_add_u64 v[208:209], v[210:211], 0, s[20:21]
	s_add_i32 m0, s17, 0x2000
	s_add_i32 s17, s26, s95
	global_load_lds_dwordx4 v[208:209], off
	v_lshl_add_u64 v[208:209], v[212:213], 0, s[20:21]
	s_mov_b32 m0, s17
	s_nop 0
	global_load_lds_dwordx4 v[208:209], off
	v_lshl_add_u64 v[208:209], v[214:215], 0, s[20:21]
	s_add_i32 m0, s17, 0x2000
	s_nop 0
	global_load_lds_dwordx4 v[208:209], off
	v_lshl_add_u64 v[208:209], s[24:25], 0, v[198:199]
	s_mov_b32 m0, s30
	s_nop 0
	global_load_lds_dwordx4 v[208:209], off
	v_lshl_add_u64 v[208:209], s[24:25], 0, v[202:203]
	s_mov_b32 m0, s31
	s_nop 0
	global_load_lds_dwordx4 v[208:209], off
	s_add_u32 s10, s10, 0x180
	s_addc_u32 s11, s11, 0
	s_add_u32 s15, s15, 0x100
	s_addc_u32 s16, s16, 0
	s_mov_b32 s17, s22
	s_cmp_ge_u32 s22, s87
	s_cbranch_scc1 .Lg_ctl_done
	s_or_b32 s22, s17, 1
	s_lshl_b64 s[34:35], s[22:23], 7
	s_add_i32 s22, s17, 2
	s_lshl_b64 s[28:29], s[22:23], 7
	s_add_i32 s24, s17, 3
	s_mov_b32 s25, s23
	s_lshl_b64 s[24:25], s[24:25], 7
	s_and_b64 vcc, exec, s[84:85]
	s_cbranch_scc1 .Lg_ctl_std
	s_add_u32 s34, s10, 0xfffffe80
	s_addc_u32 s35, s11, -1
	s_add_u32 s28, s10, 0xffffff80
	s_addc_u32 s29, s11, -1
	s_mov_b64 s[24:25], s[10:11]
.Lg_ctl_std:
	s_add_u32 s28, s8, s28
	s_addc_u32 s29, s9, s29
	s_add_u32 s24, s8, s24
	s_addc_u32 s25, s9, s25
	s_cmp_eq_u32 s63, s17
	s_cselect_b32 s28, s2, s28
	s_cselect_b32 s29, s3, s29
	s_cselect_b32 s24, s0, s24
	s_cselect_b32 s25, s1, s25
	s_cselect_b32 s44, s82, s15
	s_cselect_b32 s45, s83, s16
.Lg_ctl_done:
	s_waitcnt vmcnt(8)
	s_waitcnt lgkmcnt(0)
	s_barrier
	s_setprio 1
	s_waitcnt lgkmcnt(0)
	v_mfma_f32_16x16x32_bf16 v[60:63], v[130:133], v[162:165], v[60:63]
	v_mfma_f32_16x16x32_bf16 v[56:59], v[138:141], v[162:165], v[56:59]
	v_mfma_f32_16x16x32_bf16 v[48:51], v[130:133], v[170:173], v[48:51]
	v_mfma_f32_16x16x32_bf16 v[40:43], v[138:141], v[170:173], v[40:43]
	v_mfma_f32_16x16x32_bf16 v[32:35], v[130:133], v[178:181], v[32:35]
	v_mfma_f32_16x16x32_bf16 v[24:27], v[138:141], v[178:181], v[24:27]
	v_mfma_f32_16x16x32_bf16 v[16:19], v[130:133], v[186:189], v[16:19]
	v_mfma_f32_16x16x32_bf16 v[8:11], v[138:141], v[186:189], v[8:11]
	v_mfma_f32_16x16x32_bf16 v[60:63], v[134:137], v[166:169], v[60:63]
	v_mfma_f32_16x16x32_bf16 v[56:59], v[142:145], v[166:169], v[56:59]
	v_mfma_f32_16x16x32_bf16 v[48:51], v[134:137], v[174:177], v[48:51]
	v_mfma_f32_16x16x32_bf16 v[40:43], v[142:145], v[174:177], v[40:43]
	v_mfma_f32_16x16x32_bf16 v[32:35], v[134:137], v[182:185], v[32:35]
	v_mfma_f32_16x16x32_bf16 v[24:27], v[142:145], v[182:185], v[24:27]
	v_mfma_f32_16x16x32_bf16 v[16:19], v[134:137], v[190:193], v[16:19]
	v_mfma_f32_16x16x32_bf16 v[8:11], v[142:145], v[190:193], v[8:11]
	s_setprio 0
	s_setprio 1
	v_mfma_f32_16x16x32_bf16 v[52:55], v[146:149], v[162:165], v[52:55]
	v_mfma_f32_16x16x32_bf16 v[44:47], v[154:157], v[162:165], v[44:47]
	v_mfma_f32_16x16x32_bf16 v[36:39], v[146:149], v[170:173], v[36:39]
	v_mfma_f32_16x16x32_bf16 v[28:31], v[154:157], v[170:173], v[28:31]
	v_mfma_f32_16x16x32_bf16 v[20:23], v[146:149], v[178:181], v[20:23]
	v_mfma_f32_16x16x32_bf16 v[12:15], v[154:157], v[178:181], v[12:15]
	v_mfma_f32_16x16x32_bf16 v[4:7], v[146:149], v[186:189], v[4:7]
	v_mfma_f32_16x16x32_bf16 v[0:3], v[154:157], v[186:189], v[0:3]
	v_mfma_f32_16x16x32_bf16 v[52:55], v[150:153], v[166:169], v[52:55]
	v_mfma_f32_16x16x32_bf16 v[44:47], v[158:161], v[166:169], v[44:47]
	v_mfma_f32_16x16x32_bf16 v[36:39], v[150:153], v[174:177], v[36:39]
	v_mfma_f32_16x16x32_bf16 v[28:31], v[158:161], v[174:177], v[28:31]
	v_mfma_f32_16x16x32_bf16 v[20:23], v[150:153], v[182:185], v[20:23]
	v_mfma_f32_16x16x32_bf16 v[12:15], v[158:161], v[182:185], v[12:15]
	v_mfma_f32_16x16x32_bf16 v[4:7], v[150:153], v[190:193], v[4:7]
	v_mfma_f32_16x16x32_bf16 v[0:3], v[158:161], v[190:193], v[0:3]
	s_setprio 0
	s_barrier
	s_cmp_ge_u32 s17, s87
	s_cbranch_scc0 .Lg_body
	s_branch .LBB0_267
